# spatial phase: bank-conflict-free swizzle of the LN(v) LDS image for the transposed 16-bit reads
# speedup vs baseline: 1.0100x; 1.0100x over previous
; #define LAS __attribute__((address_space(3)))
; __device__ __forceinline__ int tid_opaque() { int t = threadIdx.x; asm volatile("" : "+v"(t)); return t; }
; __device__ __forceinline__ int sgpr_opaque(int x) { asm volatile("" : "+s"(x)); return x; }
; #define INP(i) ((const float*)ldp(T, (i)))
; __device__ __forceinline__ void spatial_phase(const PT& T, int a, LAS unsigned char* lds, int vc) {
;     const int tid = tid_opaque(), lane = tid & 63, wid = __builtin_amdgcn_readfirstlane(tid >> 6), fr = lane & 15, fq = lane >> 4;
;     const bf16_t* __restrict__ Z = (const bf16_t*)((unsigned char*)OUTP); bf16_t* __restrict__ Y = (bf16_t*)(WSP + WS_T2);
;     const float* __restrict__ vst = (const float*)(WSP + WS_VST + (size_t)a * MiB);
;     const float* __restrict__ gv = INP(5) + a * D; const float* __restrict__ bs = INP(7) + a * D;
;     const bf16_t* __restrict__ Wm = (const bf16_t*)(WSP + WS_W) + WO_A_S0 + (size_t)a * WO_A_STRIDE;
;     constexpr int LDW = 136;
;     LAS bf16_t* sW = (LAS bf16_t*)lds; LAS bf16_t* sV = (LAS bf16_t*)(lds + 128 * LDW * 2);
;     const int R8 = sgpr_opaque(gridDim.x) >> 3, vx = sgpr_opaque(vc) & 7, vr = sgpr_opaque(vc) >> 3;
;     const int wi = wid >> 2, wc = wid & 3, ib = wi * 64, cb = wc * 32;
;     const int jq = tid >> 4, c8 = (tid & 15) * 8;
;     for (int ti = vr; ti < 256; ti += R8) {
;         const int t = 256 * vx + ti, nb = t >> 3, g = t & 7;
;         u32x4 wreg[4], vreg[4]; f32x4 p1[4], p2[4];
; #pragma unroll
;         for (int q = 0; q < 4; ++q) { const int j = jq + 32 * q; const size_t row = (size_t)nb * 128 + j;
;             wreg[q] = *(const u32x4*)(Wm + (size_t)g * 16384 + j * 128 + c8);
;             vreg[q] = *(const u32x4*)(Z + row * 2048 + 1024 + g * 128 + c8);
;             p1[q] = *(const f32x4*)(vst + 8 * row); p2[q] = *(const f32x4*)(vst + 8 * row + 4); }
;         const f32x4 g0 = *(const f32x4*)(gv + g * 128 + c8), g1 = *(const f32x4*)(gv + g * 128 + c8 + 4);
.LBB0_795:
	v_readlane_b32 s0, v254, 8
	v_mov_b32_e32 v0, v220
	v_readlane_b32 s4, v254, 13
	v_mov_b32_e32 v2, s0
	s_waitcnt lgkmcnt(0)
	ds_read2_b64 v[2:5], v2 offset1:1
	v_readlane_b32 s0, v254, 12
	s_mov_b32 s15, s68
	v_readfirstlane_b32 s10, v0
	v_mov_b32_e32 v6, s0
	ds_read_b64 v[6:7], v6
	s_waitcnt lgkmcnt(0)
	v_readfirstlane_b32 s0, v2
	v_mov_b32_e32 v2, s4
	v_readfirstlane_b32 s1, v3
	ds_read_b64 v[2:3], v2
	v_readlane_b32 s4, v254, 22
	s_mov_b32 s18, s4
	s_ashr_i32 s4, s4, 3
	v_readfirstlane_b32 s16, v5
	v_readfirstlane_b32 s19, v4
	v_readfirstlane_b32 s11, v7
	v_readfirstlane_b32 s17, v6
	s_waitcnt lgkmcnt(0)
	v_readfirstlane_b32 s9, v3
	s_cmpk_gt_i32 s4, 0xff
	v_readfirstlane_b32 s8, v2
	s_cbranch_scc1 .LBB0_800
	s_add_u32 s5, s19, 0x15000000
	v_readlane_b32 s6, v254, 27
	s_addc_u32 s14, s16, 0
	v_readlane_b32 s7, v254, 28
	s_mov_b32 s28, s6
	s_ashr_i32 s29, s6, 31
	s_lshl_b64 s[6:7], s[28:29], 20
	s_add_u32 s6, s19, s6
	s_addc_u32 s7, s16, s7
	s_add_u32 s6, s6, 0x19500000
	s_addc_u32 s7, s7, 0
	s_lshl_b32 s20, s28, 10
	s_ashr_i32 s21, s20, 31
	s_lshl_b64 s[20:21], s[20:21], 2
	s_add_u32 s8, s8, s20
	s_addc_u32 s9, s9, s21
	s_lshr_b32 s22, s10, 1
	s_ashr_i32 s25, s10, 2
	s_ashr_i32 s15, s15, 3
	s_and_b32 s24, s22, 0x60
	s_and_b32 s26, s25, 0xffffffc0
	s_mul_i32 s22, s28, 0x640000
	s_mul_hi_i32 s23, s28, 0x640000
	s_add_u32 s22, s19, s22
	s_addc_u32 s23, s16, s23
	s_add_u32 s20, s17, s20
	s_addc_u32 s21, s11, s21
	s_lshl_b32 s11, s18, 8
	v_lshlrev_b32_e32 v2, 3, v0
	s_and_b32 s16, s11, 0x700
	v_ashrrev_i32_e32 v34, 4, v0
	v_and_b32_e32 v2, 0x78, v2
	s_cmpk_lt_u32 s10, 0x100
	s_movk_i32 s11, 0x110
	v_bfe_u32 v3, v0, 4, 2
	v_and_b32_e32 v12, 15, v0
	v_lshlrev_b32_e32 v0, 1, v2
	s_cselect_b32 s17, 2, 4
	v_mul_lo_u32 v6, v34, s11
	s_and_b32 s10, s10, 0xc0
	v_lshl_add_u64 v[4:5], s[22:23], 0, v[0:1]
	v_add3_u32 v91, 0, v0, v6
	v_mov_b32_e32 v0, s10
	s_movk_i32 s10, 0x880
	v_or_b32_e32 v40, s26, v12
	v_mad_u32_u24 v0, v3, s10, v0
	v_ashrrev_i32_e32 v41, 31, v40
	v_lshl_or_b32 v0, v12, 1, v0
	v_readlane_b32 s10, v254, 14
	v_lshlrev_b64 v[56:57], 12, v[40:41]
	v_lshlrev_b64 v[64:65], 11, v[40:41]
	v_add_u32_e32 v41, s10, v0
	v_and_b32_e32 v217, 0xc0, v220
	v_lshl_or_b32 v217, v12, 1, v217
	v_lshl_add_u32 v217, v3, 5, v217
	v_and_b32_e32 v218, 0xff, v217
	v_add_u32_e32 v217, 32, v217
	v_and_b32_e32 v217, 0xff, v217
	v_mul_u32_u24_e32 v216, 0x880, v3
	v_add_u32_e32 v216, s10, v216
	v_add_u32_e32 v215, v216, v218
	v_add_u32_e32 v216, v216, v217
	v_bfe_u32 v217, v34, 3, 2
	v_lshlrev_b32_e32 v218, 1, v2
	v_lshl_add_u32 v217, v217, 5, v218
	v_and_b32_e32 v217, 0xff, v217
	v_add_u32_e32 v214, v6, v217
	s_lshr_b32 s10, s25, 6
	s_mov_b64 s[18:19], 0xa00000
	s_mulk_i32 s10, 0x4400
	v_lshl_add_u64 v[36:37], v[4:5], 0, s[18:19]
	v_lshlrev_b32_e32 v4, 2, v2
	v_mov_b32_e32 v5, v1
	v_add_u32_e32 v44, 32, v34
	v_add_u32_e32 v48, 64, v34
	v_add_u32_e32 v52, 0x60, v34
	v_or_b32_e32 v6, 16, v40
	v_or_b32_e32 v8, 32, v40
	v_or_b32_e32 v10, 48, v40
	v_mov_b32_e32 v0, s10
	v_lshl_add_u64 v[38:39], s[20:21], 0, v[4:5]
	v_lshlrev_b32_e32 v4, 2, v3
	v_lshlrev_b32_e32 v5, 4, v3
	v_lshlrev_b32_e32 v42, 7, v34
	v_lshlrev_b32_e32 v46, 7, v44
	v_lshlrev_b32_e32 v50, 7, v48
	v_lshlrev_b32_e32 v54, 7, v52
	v_ashrrev_i32_e32 v7, 31, v6
	v_ashrrev_i32_e32 v9, 31, v8
	v_ashrrev_i32_e32 v11, 31, v10
	v_mad_u32_u24 v0, v12, s11, v0
	v_or_b32_e32 v90, s24, v4
	v_ashrrev_i32_e32 v35, 31, v34
	v_ashrrev_i32_e32 v43, 31, v42
	v_ashrrev_i32_e32 v45, 31, v44
	v_ashrrev_i32_e32 v47, 31, v46
	v_ashrrev_i32_e32 v49, 31, v48
	v_ashrrev_i32_e32 v51, 31, v50
	v_ashrrev_i32_e32 v53, 31, v52
	v_ashrrev_i32_e32 v55, 31, v54
	v_lshlrev_b64 v[58:59], 12, v[6:7]
	v_lshlrev_b64 v[60:61], 12, v[8:9]
	v_lshlrev_b64 v[62:63], 12, v[10:11]
	v_lshlrev_b64 v[66:67], 11, v[6:7]
	v_lshlrev_b64 v[68:69], 11, v[8:9]
	v_lshlrev_b64 v[70:71], 11, v[10:11]
	v_add3_u32 v92, v0, v5, 0
	v_lshlrev_b32_e32 v0, 1, v2
	s_lshl_b32 s18, s24, 1
	v_lshlrev_b32_e32 v72, 1, v4
	s_add_i32 s10, s4, s16
	s_ashr_i32 s10, s10, 3
	s_ashr_i32 s11, s10, 31
	s_lshl_b64 s[20:21], s[10:11], 7
	v_lshl_add_u64 v[120:121], s[20:21], 0, v[34:35]
	v_lshlrev_b64 v[122:123], 5, v[120:121]
	v_lshl_add_u64 v[122:123], s[6:7], 0, v[122:123]
	global_load_dwordx4 v[140:143], v[122:123], off
	global_load_dwordx4 v[144:147], v[122:123], off offset:16
	s_and_b32 s19, s4, 7
	s_lshl_b32 s46, s19, 15
	v_lshlrev_b64 v[120:121], 12, v[120:121]
	v_lshl_add_u64 v[124:125], v[36:37], 0, s[46:47]
	v_lshl_add_u64 v[120:121], s[0:1], 0, v[120:121]
	s_lshl_b32 s46, s19, 8
	v_lshl_add_u64 v[120:121], v[120:121], 0, s[46:47]
	v_lshl_add_u64 v[120:121], v[120:121], 0, v[0:1]
	global_load_dwordx4 v[148:151], v[120:121], off offset:2048
	s_mov_b32 s23, s47
	s_lshl_b32 s22, s19, 9
	v_lshl_add_u64 v[120:121], v[38:39], 0, s[22:23]
	global_load_dwordx4 v[128:131], v[120:121], off
	s_nop 0
	global_load_dwordx4 v[120:123], v[120:121], off offset:16
	v_lshl_add_u64 v[126:127], v[42:43], 1, v[124:125]
	v_lshl_add_u64 v[132:133], v[46:47], 1, v[124:125]
	v_lshl_add_u64 v[168:169], s[20:21], 0, v[44:45]
	global_load_dwordx4 v[152:155], v[126:127], off
	global_load_dwordx4 v[156:159], v[132:133], off
	v_lshlrev_b64 v[126:127], 5, v[168:169]
	v_lshl_add_u64 v[126:127], s[6:7], 0, v[126:127]
	global_load_dwordx4 v[160:163], v[126:127], off
	v_lshl_add_u64 v[134:135], v[50:51], 1, v[124:125]
	v_lshl_add_u64 v[124:125], v[54:55], 1, v[124:125]
	global_load_dwordx4 v[136:139], v[134:135], off
	global_load_dwordx4 v[164:167], v[126:127], off offset:16
	s_nop 0
	global_load_dwordx4 v[124:127], v[124:125], off
	v_lshlrev_b64 v[168:169], 12, v[168:169]
	v_lshl_add_u64 v[168:169], s[0:1], 0, v[168:169]
	v_lshl_add_u64 v[132:133], s[20:21], 0, v[48:49]
	v_lshl_add_u64 v[168:169], v[168:169], 0, s[46:47]
	v_lshlrev_b64 v[170:171], 12, v[132:133]
	v_lshl_add_u64 v[168:169], v[168:169], 0, v[0:1]
	v_lshl_add_u64 v[174:175], s[0:1], 0, v[170:171]
	global_load_dwordx4 v[168:171], v[168:169], off offset:2048
	v_lshl_add_u64 v[134:135], s[20:21], 0, v[52:53]
	v_lshlrev_b64 v[132:133], 5, v[132:133]
	v_lshlrev_b64 v[172:173], 12, v[134:135]
	v_lshl_add_u64 v[132:133], s[6:7], 0, v[132:133]
	v_lshl_add_u64 v[180:181], s[0:1], 0, v[172:173]
	v_lshl_add_u64 v[188:189], v[174:175], 0, s[46:47]
	global_load_dwordx4 v[172:175], v[132:133], off
	global_load_dwordx4 v[176:179], v[132:133], off offset:16
	v_lshlrev_b64 v[134:135], 5, v[134:135]
	v_lshl_add_u64 v[134:135], s[6:7], 0, v[134:135]
	v_lshl_add_u64 v[132:133], v[180:181], 0, s[46:47]
	global_load_dwordx4 v[180:183], v[134:135], off
	global_load_dwordx4 v[184:187], v[134:135], off offset:16
	v_lshl_add_u64 v[134:135], v[188:189], 0, v[0:1]
	v_lshl_add_u64 v[132:133], v[132:133], 0, v[0:1]
	global_load_dwordx4 v[188:191], v[134:135], off offset:2048
	s_nop 0
	global_load_dwordx4 v[132:135], v[132:133], off offset:2048
	s_waitcnt vmcnt(0)
; #define LAS __attribute__((address_space(3)))
; __device__ __forceinline__ unsigned pk2(float lo, float hi) { return pg8::cvt_pk_bf16(lo, hi); }
; __device__ __forceinline__ void spatial_phase(const PT& T, int a, LAS unsigned char* lds, int vc) {
;     ...
;         for (int q = 0; q < 4; ++q) { const int j = jq + 32 * q;
;             const float s1 = (p1[q].x + p1[q].y) + (p1[q].z + p1[q].w), s2 = (p2[q].x + p2[q].y) + (p2[q].z + p2[q].w);
;             const float mu = s1 * (1.0f / D); float var = s2 * (1.0f / D) - mu * mu; var = var > 0.f ? var : 0.f; const float rs = __builtin_amdgcn_rsqf(var + EPS);
;             const u32x4 raw = vreg[q];
;             u32x4 o; o.x = pk2((bflo(raw.x) - mu) * rs * g0.x, (bfhi(raw.x) - mu) * rs * g0.y); o.y = pk2((bflo(raw.y) - mu) * rs * g0.z, (bfhi(raw.y) - mu) * rs * g0.w);
;             o.z = pk2((bflo(raw.z) - mu) * rs * g1.x, (bfhi(raw.z) - mu) * rs * g1.y); o.w = pk2((bflo(raw.w) - mu) * rs * g1.z, (bfhi(raw.w) - mu) * rs * g1.w);
;             *(LAS u32x4*)(sV + j * LDW + c8) = o; *(LAS u32x4*)(sW + j * LDW + c8) = wreg[q]; }
.LBB0_797:
	s_add_i32 s10, s4, s16
	s_ashr_i32 s10, s10, 3
	s_ashr_i32 s11, s10, 31
	s_and_b32 s19, s4, 7
	s_lshl_b32 s46, s19, 8
	s_mov_b32 s20, 0x3a800000
	s_lshl_b32 s19, s19, 7
	s_waitcnt vmcnt(8) lgkmcnt(0)
	v_mov_b32_e32 v192, v141
	v_mov_b32_e32 v193, v142
	v_mov_b32_e32 v141, v143
	v_pk_add_f32 v[140:141], v[192:193], v[140:141]
	v_add_f32_e32 v142, v144, v145
	v_add_f32_e32 v144, v146, v147
	v_mov_b32_e32 v143, v140
	v_mov_b32_e32 v145, v141
	v_pk_add_f32 v[140:141], v[142:143], v[144:145]
	v_lshlrev_b32_e32 v146, 16, v148
	v_pk_mul_f32 v[142:143], v[140:141], s[20:21] op_sel_hi:[1,0]
	v_and_b32_e32 v147, 0xffff0000, v148
	v_fma_f32 v140, -v143, v143, v142
	v_max_f32_e32 v140, 0, v140
	v_add_f32_e32 v140, 0x358637bd, v140
	v_rsq_f32_e32 v145, v140
	v_lshlrev_b32_e32 v148, 16, v149
	v_lshlrev_b32_e32 v73, 16, v150
	v_and_b32_e32 v149, 0xffff0000, v149
	v_and_b32_e32 v150, 0xffff0000, v150
	v_sub_f32_e32 v141, v146, v143
	v_sub_f32_e32 v142, v147, v143
	v_sub_f32_e32 v144, v148, v143
	v_sub_f32_e32 v146, v73, v143
	v_sub_f32_e32 v140, v149, v143
	v_sub_f32_e32 v147, v150, v143
	v_mul_f32_e32 v141, v141, v145
	v_mul_f32_e32 v142, v142, v145
	v_mul_f32_e32 v144, v144, v145
	v_mul_f32_e32 v146, v146, v145
	v_mul_f32_e32 v140, v140, v145
	v_mul_f32_e32 v147, v147, v145
	v_mul_f32_e32 v141, v141, v128
	v_mul_f32_e32 v142, v142, v129
	v_mul_f32_e32 v144, v144, v130
	v_mul_f32_e32 v146, v146, v120
	v_mul_f32_e32 v148, v140, v131
	v_mul_f32_e32 v147, v147, v121
	v_cvt_pk_bf16_f32 v140, v141, v142
	v_cvt_pk_bf16_f32 v141, v144, v148
	v_cvt_pk_bf16_f32 v142, v146, v147
	v_lshlrev_b32_e32 v144, 16, v151
	v_and_b32_e32 v146, 0xffff0000, v151
	v_sub_f32_e32 v144, v144, v143
	v_sub_f32_e32 v143, v146, v143
	v_mul_f32_e32 v143, v143, v145
	v_mul_f32_e32 v144, v144, v145
	v_mul_f32_e32 v143, v143, v123
	v_mul_f32_e32 v144, v144, v122
	v_cvt_pk_bf16_f32 v143, v144, v143
	ds_write_b128 v214, v[140:143] offset:34816
	v_mov_b32_e32 v140, v161
	v_mov_b32_e32 v141, v162
	v_mov_b32_e32 v161, v163
	v_pk_add_f32 v[140:141], v[140:141], v[160:161]
	v_add_f32_e32 v142, v164, v165
	v_add_f32_e32 v144, v166, v167
	v_mov_b32_e32 v143, v140
	v_mov_b32_e32 v145, v141
	v_pk_add_f32 v[140:141], v[142:143], v[144:145]
	ds_write_b128 v91, v[152:155]
	v_pk_mul_f32 v[142:143], v[140:141], s[20:21] op_sel_hi:[1,0]
	v_and_b32_e32 v141, 0xffff0000, v168
	v_fma_f32 v140, -v143, v143, v142
	v_max_f32_e32 v140, 0, v140
	v_add_f32_e32 v140, 0x358637bd, v140
	v_rsq_f32_e32 v144, v140
	v_lshlrev_b32_e32 v140, 16, v168
	v_sub_f32_e32 v140, v140, v143
	v_sub_f32_e32 v141, v141, v143
	v_mul_f32_e32 v140, v140, v144
	v_mul_f32_e32 v141, v141, v144
	v_mul_f32_e32 v140, v128, v140
	v_mul_f32_e32 v141, v129, v141
	v_cvt_pk_bf16_f32 v140, v140, v141
	v_lshlrev_b32_e32 v141, 16, v169
	v_and_b32_e32 v142, 0xffff0000, v169
	v_sub_f32_e32 v141, v141, v143
	v_sub_f32_e32 v142, v142, v143
	v_mul_f32_e32 v141, v141, v144
	v_mul_f32_e32 v142, v142, v144
	v_mul_f32_e32 v141, v130, v141
	v_mul_f32_e32 v142, v131, v142
	v_cvt_pk_bf16_f32 v141, v141, v142
	v_lshlrev_b32_e32 v142, 16, v170
	v_and_b32_e32 v145, 0xffff0000, v170
	v_sub_f32_e32 v142, v142, v143
	v_sub_f32_e32 v145, v145, v143
	v_mul_f32_e32 v142, v142, v144
	v_mul_f32_e32 v145, v145, v144
	v_mul_f32_e32 v142, v142, v120
	v_mul_f32_e32 v145, v145, v121
	v_cvt_pk_bf16_f32 v142, v142, v145
	v_lshlrev_b32_e32 v145, 16, v171
	v_and_b32_e32 v146, 0xffff0000, v171
	v_sub_f32_e32 v145, v145, v143
	v_sub_f32_e32 v143, v146, v143
	v_mul_f32_e32 v143, v143, v144
	v_mul_f32_e32 v145, v145, v144
	v_mul_f32_e32 v143, v143, v123
	v_mul_f32_e32 v145, v145, v122
	v_cvt_pk_bf16_f32 v143, v145, v143
	ds_write_b128 v214, v[140:143] offset:43520
	v_mov_b32_e32 v140, v173
	v_mov_b32_e32 v141, v174
	v_mov_b32_e32 v173, v175
	v_pk_add_f32 v[140:141], v[140:141], v[172:173]
	v_add_f32_e32 v142, v176, v177
	v_add_f32_e32 v144, v178, v179
	v_mov_b32_e32 v143, v140
	v_mov_b32_e32 v145, v141
	v_pk_add_f32 v[140:141], v[142:143], v[144:145]
	ds_write_b128 v91, v[156:159] offset:8704
	v_pk_mul_f32 v[142:143], v[140:141], s[20:21] op_sel_hi:[1,0]
	v_and_b32_e32 v141, 0xffff0000, v188
	v_fma_f32 v140, -v143, v143, v142
	v_max_f32_e32 v140, 0, v140
	v_add_f32_e32 v140, 0x358637bd, v140
	v_rsq_f32_e32 v144, v140
	v_lshlrev_b32_e32 v140, 16, v188
	v_sub_f32_e32 v140, v140, v143
	v_sub_f32_e32 v141, v141, v143
	v_mul_f32_e32 v140, v140, v144
	v_mul_f32_e32 v141, v141, v144
	v_mul_f32_e32 v140, v128, v140
	v_mul_f32_e32 v141, v129, v141
	v_cvt_pk_bf16_f32 v140, v140, v141
	v_lshlrev_b32_e32 v141, 16, v189
	v_and_b32_e32 v142, 0xffff0000, v189
	v_sub_f32_e32 v141, v141, v143
	v_sub_f32_e32 v142, v142, v143
	v_mul_f32_e32 v141, v141, v144
	v_mul_f32_e32 v142, v142, v144
	v_mul_f32_e32 v141, v130, v141
	v_mul_f32_e32 v142, v131, v142
	v_cvt_pk_bf16_f32 v141, v141, v142
	v_lshlrev_b32_e32 v142, 16, v190
	v_and_b32_e32 v145, 0xffff0000, v190
	v_sub_f32_e32 v142, v142, v143
	v_sub_f32_e32 v145, v145, v143
	v_mul_f32_e32 v142, v142, v144
	v_mul_f32_e32 v145, v145, v144
	v_mul_f32_e32 v142, v120, v142
	v_mul_f32_e32 v145, v121, v145
	v_cvt_pk_bf16_f32 v142, v142, v145
	v_lshlrev_b32_e32 v145, 16, v191
	v_and_b32_e32 v146, 0xffff0000, v191
	v_sub_f32_e32 v145, v145, v143
	v_sub_f32_e32 v143, v146, v143
	v_mul_f32_e32 v143, v143, v144
	v_mul_f32_e32 v145, v145, v144
	v_mul_f32_e32 v143, v123, v143
	v_mul_f32_e32 v145, v122, v145
	v_cvt_pk_bf16_f32 v143, v145, v143
	ds_write_b128 v214, v[140:143] offset:52224
	v_mov_b32_e32 v140, v181
	v_mov_b32_e32 v141, v182
	v_mov_b32_e32 v181, v183
	v_pk_add_f32 v[140:141], v[140:141], v[180:181]
	v_add_f32_e32 v142, v184, v185
; #define LAS __attribute__((address_space(3)))
; __device__ __forceinline__ unsigned pk2(float lo, float hi) { return pg8::cvt_pk_bf16(lo, hi); }
; __device__ __forceinline__ void spatial_phase(const PT& T, int a, LAS unsigned char* lds, int vc) {
;     ...
;         for (int q = 0; q < 4; ++q) { const int j = jq + 32 * q; const size_t row = (size_t)nb * 128 + j;
;             wreg[q] = *(const u32x4*)(Wm + (size_t)g * 16384 + j * 128 + c8);
;             vreg[q] = *(const u32x4*)(Z + row * 2048 + 1024 + g * 128 + c8);
;             p1[q] = *(const f32x4*)(vst + 8 * row); p2[q] = *(const f32x4*)(vst + 8 * row + 4); }
;         const f32x4 g0 = *(const f32x4*)(gv + g * 128 + c8), g1 = *(const f32x4*)(gv + g * 128 + c8 + 4);
;     ...
;             const float s1 = (p1[q].x + p1[q].y) + (p1[q].z + p1[q].w), s2 = (p2[q].x + p2[q].y) + (p2[q].z + p2[q].w);
;             const float mu = s1 * (1.0f / D); float var = s2 * (1.0f / D) - mu * mu; var = var > 0.f ? var : 0.f; const float rs = __builtin_amdgcn_rsqf(var + EPS);
;             const u32x4 raw = vreg[q];
;             u32x4 o; o.x = pk2((bflo(raw.x) - mu) * rs * g0.x, (bfhi(raw.x) - mu) * rs * g0.y); o.y = pk2((bflo(raw.y) - mu) * rs * g0.z, (bfhi(raw.y) - mu) * rs * g0.w);
;             o.z = pk2((bflo(raw.z) - mu) * rs * g1.x, (bfhi(raw.z) - mu) * rs * g1.y); o.w = pk2((bflo(raw.w) - mu) * rs * g1.z, (bfhi(raw.w) - mu) * rs * g1.w);
;             *(LAS u32x4*)(sV + j * LDW + c8) = o; *(LAS u32x4*)(sW + j * LDW + c8) = wreg[q]; }
;         u32x2 uu[4][2]; float bsv[4];
; #pragma unroll
;         for (int mt = 0; mt < 4; ++mt) { const int i = ib + 16 * mt + fr; bsv[mt] = bs[g * 128 + i];
; #pragma unroll
;             for (int n = 0; n < 2; ++n) uu[mt][n] = *(const u32x2*)(Z + ((size_t)nb * 128 + i) * 2048 + g * 128 + cb + 16 * n + 4 * fq); }
;         __syncthreads();
;         f32x4 acc[4][2];
; #pragma unroll
;         for (int mt = 0; mt < 4; ++mt)
; #pragma unroll
;             for (int n = 0; n < 2; ++n) acc[mt][n] = (f32x4){0.f, 0.f, 0.f, 0.f};
	v_add_f32_e32 v144, v186, v187
	v_mov_b32_e32 v143, v140
	v_mov_b32_e32 v145, v141
	v_pk_add_f32 v[140:141], v[142:143], v[144:145]
	ds_write_b128 v91, v[136:139] offset:17408
	v_pk_mul_f32 v[140:141], v[140:141], s[20:21] op_sel_hi:[1,0]
	v_lshlrev_b32_e32 v136, 16, v132
	v_fma_f32 v140, -v141, v141, v140
	v_max_f32_e32 v140, 0, v140
	v_add_f32_e32 v140, 0x358637bd, v140
	v_rsq_f32_e32 v140, v140
	v_and_b32_e32 v132, 0xffff0000, v132
	v_sub_f32_e32 v136, v136, v141
	v_sub_f32_e32 v132, v132, v141
	v_mul_f32_e32 v136, v136, v140
	v_mul_f32_e32 v132, v132, v140
	v_mul_f32_e32 v128, v128, v136
	v_mul_f32_e32 v129, v129, v132
	v_cvt_pk_bf16_f32 v128, v128, v129
	v_lshlrev_b32_e32 v129, 16, v133
	v_sub_f32_e32 v129, v129, v141
	v_mul_f32_e32 v129, v129, v140
	v_mul_f32_e32 v129, v130, v129
	v_and_b32_e32 v130, 0xffff0000, v133
	v_sub_f32_e32 v130, v130, v141
	v_mul_f32_e32 v130, v130, v140
	v_mul_f32_e32 v130, v131, v130
	v_cvt_pk_bf16_f32 v129, v129, v130
	v_lshlrev_b32_e32 v130, 16, v134
	v_sub_f32_e32 v130, v130, v141
	v_mul_f32_e32 v130, v130, v140
	v_mul_f32_e32 v120, v120, v130
	v_and_b32_e32 v130, 0xffff0000, v134
	v_sub_f32_e32 v130, v130, v141
	s_lshl_b64 s[20:21], s[10:11], 19
	v_mul_f32_e32 v130, v130, v140
	s_add_u32 s20, s0, s20
	v_mul_f32_e32 v121, v121, v130
	s_addc_u32 s21, s1, s21
	v_cvt_pk_bf16_f32 v130, v120, v121
	v_lshlrev_b32_e32 v120, 16, v135
	v_and_b32_e32 v121, 0xffff0000, v135
	s_add_u32 s20, s20, s46
	v_sub_f32_e32 v120, v120, v141
	v_sub_f32_e32 v121, v121, v141
	s_addc_u32 s21, s21, 0
	v_mul_f32_e32 v120, v120, v140
	v_mul_f32_e32 v121, v121, v140
	s_add_u32 s20, s20, s18
	v_mul_f32_e32 v120, v122, v120
	v_mul_f32_e32 v121, v123, v121
	s_addc_u32 s21, s21, 0
	v_mov_b32_e32 v73, v1
	v_cvt_pk_bf16_f32 v131, v120, v121
	ds_write_b128 v214, v[128:131] offset:60928
	ds_write_b128 v91, v[124:127] offset:26112
	v_lshl_add_u64 v[2:3], s[20:21], 0, v[72:73]
	v_add_u32_e32 v4, s19, v40
	v_ashrrev_i32_e32 v5, 31, v4
	v_lshl_add_u64 v[6:7], v[2:3], 0, v[56:57]
	v_lshl_add_u64 v[4:5], v[4:5], 2, s[8:9]
	v_lshl_add_u64 v[8:9], v[2:3], 0, v[58:59]
	global_load_dwordx2 v[88:89], v[6:7], off
	global_load_dwordx2 v[86:87], v[6:7], off offset:32
	global_load_dwordx2 v[84:85], v[8:9], off
	global_load_dwordx2 v[82:83], v[8:9], off offset:32
	v_lshl_add_u64 v[6:7], v[2:3], 0, v[60:61]
	global_load_dword v95, v[4:5], off
	global_load_dword v94, v[4:5], off offset:64
	global_load_dword v93, v[4:5], off offset:128
	global_load_dword v73, v[4:5], off offset:192
	v_lshl_add_u64 v[2:3], v[2:3], 0, v[62:63]
	global_load_dwordx2 v[80:81], v[6:7], off
	global_load_dwordx2 v[78:79], v[6:7], off offset:32
	global_load_dwordx2 v[76:77], v[2:3], off
	global_load_dwordx2 v[74:75], v[2:3], off offset:32
	v_mov_b32_e32 v2, 0
	v_mov_b32_e32 v96, v92
	v_mov_b32_e32 v97, v215
	v_mov_b32_e32 v217, v216
	s_mov_b32 s20, s17
	v_mov_b32_e32 v3, v2
	v_mov_b32_e32 v4, v2
	v_mov_b32_e32 v5, v2
	v_mov_b32_e32 v6, v2
	v_mov_b32_e32 v7, v2
	v_mov_b32_e32 v8, v2
	v_mov_b32_e32 v9, v2
	v_mov_b32_e32 v10, v2
	v_mov_b32_e32 v11, v2
	v_mov_b32_e32 v12, v2
	v_mov_b32_e32 v13, v2
	v_mov_b32_e32 v14, v2
	v_mov_b32_e32 v15, v2
	v_mov_b32_e32 v16, v2
	v_mov_b32_e32 v17, v2
	v_mov_b32_e32 v18, v2
	v_mov_b32_e32 v19, v2
	v_mov_b32_e32 v20, v2
	v_mov_b32_e32 v21, v2
	v_mov_b32_e32 v22, v2
	v_mov_b32_e32 v23, v2
	v_mov_b32_e32 v24, v2
	v_mov_b32_e32 v25, v2
	v_mov_b32_e32 v26, v2
	v_mov_b32_e32 v27, v2
	v_mov_b32_e32 v28, v2
	v_mov_b32_e32 v29, v2
	v_mov_b32_e32 v30, v2
	v_mov_b32_e32 v31, v2
	v_mov_b32_e32 v32, v2
	v_mov_b32_e32 v33, v2
	s_waitcnt lgkmcnt(0)
	s_barrier
	s_add_i32 s24, s4, s15
	s_cmpk_gt_i32 s24, 0xff
	s_cbranch_scc1 .Lsp_nopf
	s_mov_b32 vcc_hi, 0
	s_add_i32 s26, s24, s16
	s_ashr_i32 s28, s26, 3
	s_ashr_i32 s29, s28, 31
	s_lshl_b64 s[28:29], s[28:29], 7
	v_lshl_add_u64 v[120:121], s[28:29], 0, v[34:35]
	v_lshlrev_b64 v[122:123], 5, v[120:121]
	v_lshl_add_u64 v[122:123], s[6:7], 0, v[122:123]
	global_load_dwordx4 v[140:143], v[122:123], off
	global_load_dwordx4 v[144:147], v[122:123], off offset:16
	s_and_b32 s25, s24, 7
	s_lshl_b32 vcc_lo, s25, 15
	v_lshlrev_b64 v[120:121], 12, v[120:121]
	v_lshl_add_u64 v[124:125], v[36:37], 0, vcc
	v_lshl_add_u64 v[120:121], s[0:1], 0, v[120:121]
	s_lshl_b32 vcc_lo, s25, 8
	v_lshl_add_u64 v[120:121], v[120:121], 0, vcc
	v_lshl_add_u64 v[120:121], v[120:121], 0, v[0:1]
	global_load_dwordx4 v[148:151], v[120:121], off offset:2048
	s_lshl_b32 vcc_lo, s25, 9
	v_lshl_add_u64 v[120:121], v[38:39], 0, vcc
	s_lshl_b32 vcc_lo, s25, 8
	global_load_dwordx4 v[128:131], v[120:121], off
	s_nop 0
	global_load_dwordx4 v[120:123], v[120:121], off offset:16
	v_lshl_add_u64 v[126:127], v[42:43], 1, v[124:125]
	v_lshl_add_u64 v[132:133], v[46:47], 1, v[124:125]
	v_lshl_add_u64 v[168:169], s[28:29], 0, v[44:45]
	global_load_dwordx4 v[152:155], v[126:127], off
	global_load_dwordx4 v[156:159], v[132:133], off
	v_lshlrev_b64 v[126:127], 5, v[168:169]
	v_lshl_add_u64 v[126:127], s[6:7], 0, v[126:127]
	global_load_dwordx4 v[160:163], v[126:127], off
	v_lshl_add_u64 v[134:135], v[50:51], 1, v[124:125]
	v_lshl_add_u64 v[124:125], v[54:55], 1, v[124:125]
	global_load_dwordx4 v[136:139], v[134:135], off
	global_load_dwordx4 v[164:167], v[126:127], off offset:16
	s_nop 0
	global_load_dwordx4 v[124:127], v[124:125], off
	v_lshlrev_b64 v[168:169], 12, v[168:169]
	v_lshl_add_u64 v[168:169], s[0:1], 0, v[168:169]
	v_lshl_add_u64 v[132:133], s[28:29], 0, v[48:49]
	v_lshl_add_u64 v[168:169], v[168:169], 0, vcc
	v_lshlrev_b64 v[170:171], 12, v[132:133]
	v_lshl_add_u64 v[168:169], v[168:169], 0, v[0:1]
	v_lshl_add_u64 v[174:175], s[0:1], 0, v[170:171]
	global_load_dwordx4 v[168:171], v[168:169], off offset:2048
	v_lshl_add_u64 v[134:135], s[28:29], 0, v[52:53]
	v_lshlrev_b64 v[132:133], 5, v[132:133]
	v_lshlrev_b64 v[172:173], 12, v[134:135]
	v_lshl_add_u64 v[132:133], s[6:7], 0, v[132:133]
	v_lshl_add_u64 v[180:181], s[0:1], 0, v[172:173]
	v_lshl_add_u64 v[188:189], v[174:175], 0, vcc
	global_load_dwordx4 v[172:175], v[132:133], off
	global_load_dwordx4 v[176:179], v[132:133], off offset:16
	v_lshlrev_b64 v[134:135], 5, v[134:135]
	v_lshl_add_u64 v[134:135], s[6:7], 0, v[134:135]
	v_lshl_add_u64 v[132:133], v[180:181], 0, vcc
	global_load_dwordx4 v[180:183], v[134:135], off
	global_load_dwordx4 v[184:187], v[134:135], off offset:16
	v_lshl_add_u64 v[134:135], v[188:189], 0, v[0:1]
	v_lshl_add_u64 v[132:133], v[132:133], 0, v[0:1]
	global_load_dwordx4 v[188:191], v[134:135], off offset:2048
	s_nop 0
	global_load_dwordx4 v[132:135], v[132:133], off offset:2048
; #define LAS __attribute__((address_space(3)))
; __device__ __forceinline__ void spatial_phase(const PT& T, int a, LAS unsigned char* lds, int vc) {
;     ...
;         for (int kk = 0; kk < nk; ++kk) {
;             bf16x8 bfr[4], af[2];
; #pragma unroll
;             for (int mt = 0; mt < 4; ++mt) bfr[mt] = *(const LAS bf16x8*)(sW + (ib + 16 * mt + fr) * LDW + kk * 32 + 8 * fq);
; #pragma unroll
;             for (int n = 0; n < 2; ++n)
; #pragma unroll
;                 for (int e = 0; e < 8; ++e) af[n][e] = (short)sV[(kk * 32 + 8 * fq + e) * LDW + cb + 16 * n + fr];
; #pragma unroll
;             for (int mt = 0; mt < 4; ++mt)
; #pragma unroll
;                 for (int n = 0; n < 2; ++n) acc[mt][n] = __builtin_amdgcn_mfma_f32_16x16x32_bf16(af[n], bfr[mt], acc[mt][n], 0, 0, 0);
;         }
.Lsp_nopf:
.LBB0_798:
	ds_read_b128 v[98:101], v96
	ds_read_b128 v[202:205], v96 offset:4352
	ds_read_b128 v[206:209], v96 offset:8704
	ds_read_b128 v[210:213], v96 offset:13056
	ds_read_u16 v102, v97 offset:272
	ds_read_u16 v103, v97 offset:544
	ds_read_u16 v106, v97 offset:816
	ds_read_u16 v107, v97
	ds_read_u16 v110, v217 offset:816
	ds_read_u16 v111, v217 offset:544
	ds_read_u16 v112, v217 offset:272
	ds_read_u16 v113, v217
	ds_read_u16 v104, v97 offset:1088
	ds_read_u16 v108, v97 offset:1360
	ds_read_u16 v105, v97 offset:1632
	ds_read_u16 v109, v97 offset:1904
	ds_read_u16 v114, v217 offset:1904
	ds_read_u16 v115, v217 offset:1632
	ds_read_u16 v116, v217 offset:1360
	ds_read_u16 v117, v217 offset:1088
	s_add_i32 s20, s20, -1
	s_waitcnt lgkmcnt(0)
	v_perm_b32 v105, v109, v105, s73
	v_perm_b32 v104, v108, v104, s73
	v_perm_b32 v103, v106, v103, s73
	v_perm_b32 v102, v102, v107, s73
	v_perm_b32 v109, v114, v115, s73
	v_perm_b32 v108, v116, v117, s73
	v_perm_b32 v107, v110, v111, s73
	v_perm_b32 v106, v112, v113, s73
	v_add_u32_e32 v97, 0x2200, v97
	v_add_u32_e32 v217, 0x2200, v217
	v_add_u32_e32 v96, 64, v96
	s_cmp_eq_u32 s20, 0
	v_mfma_f32_16x16x32_bf16 v[30:33], v[102:105], v[98:101], v[30:33]
	v_mfma_f32_16x16x32_bf16 v[26:29], v[106:109], v[98:101], v[26:29]
	v_mfma_f32_16x16x32_bf16 v[22:25], v[102:105], v[202:205], v[22:25]
	v_mfma_f32_16x16x32_bf16 v[18:21], v[106:109], v[202:205], v[18:21]
	v_mfma_f32_16x16x32_bf16 v[14:17], v[102:105], v[206:209], v[14:17]
	v_mfma_f32_16x16x32_bf16 v[10:13], v[106:109], v[206:209], v[10:13]
	v_mfma_f32_16x16x32_bf16 v[6:9], v[102:105], v[210:213], v[6:9]
	v_mfma_f32_16x16x32_bf16 v[2:5], v[106:109], v[210:213], v[2:5]
	s_cbranch_scc0 .LBB0_798
	s_cmpk_gt_i32 s24, 0xff
	s_cbranch_scc1 .Lsp_w0
	s_waitcnt vmcnt(18)
	s_branch .Lsp_epi
